# FFT: next channel's operand loads requested during the current channel (48 spare VGPRs)
# baseline (speedup 1.0000x reference)
.LBB0_1374:
	s_or_b64 exec, exec, s[0:1]
	s_cmpk_gt_i32 s2, 0x7ff
	s_waitcnt lgkmcnt(0)
	s_barrier
	s_cbranch_scc1 .LBB0_1413
	v_add_u32_e32 v147, 0x200, v32
	v_lshlrev_b32_e32 v1, 3, v32
	s_add_i32 s25, 0, 0x10000
	v_add_u32_e32 v150, 0x400, v32
	v_lshlrev_b32_e32 v6, 5, v147
	v_lshlrev_b32_e32 v34, 1, v32
	s_mov_b32 s4, 0
	v_add_u32_e32 v33, s25, v1
	v_add_u32_e32 v145, 0, v1
	v_add_u32_e32 v153, 0x600, v32
	v_add_u32_e32 v1, 0x800, v32
	v_add_u32_e32 v2, 0xa00, v32
	v_add_u32_e32 v3, 0xc00, v32
	v_add_u32_e32 v4, 0xe00, v32
	v_add_u32_e32 v165, 0, v6
	v_add_u32_e32 v166, s25, v6
	v_lshlrev_b32_e32 v6, 5, v150
	v_lshlrev_b32_e32 v0, 4, v32
	v_lshlrev_b32_e32 v144, 5, v32
	v_sub_u32_e32 v36, 0x2000, v34
	v_sub_u32_e32 v38, 0x1fff, v34
	v_add_u32_e32 v40, 0x400, v34
	v_sub_u32_e32 v42, 0x1c00, v34
	v_sub_u32_e32 v44, 0x1bff, v34
	v_add_u32_e32 v46, 0x800, v34
	v_sub_u32_e32 v48, 0x1800, v34
	v_sub_u32_e32 v50, 0x17ff, v34
	v_add_u32_e32 v52, 0xc00, v34
	v_sub_u32_e32 v54, 0x1400, v34
	v_sub_u32_e32 v56, 0x13ff, v34
	v_add_u32_e32 v58, 0x1000, v34
	v_sub_u32_e32 v60, 0x1000, v34
	v_sub_u32_e32 v62, 0xfff, v34
	v_add_u32_e32 v64, 0x1400, v34
	v_sub_u32_e32 v66, 0xc00, v34
	v_sub_u32_e32 v68, 0xbff, v34
	v_add_u32_e32 v70, 0x1800, v34
	v_sub_u32_e32 v72, 0x800, v34
	v_sub_u32_e32 v74, 0x7ff, v34
	v_add_u32_e32 v76, 0x1c00, v34
	v_sub_u32_e32 v78, 0x400, v34
	v_sub_u32_e32 v80, 0x3ff, v34
	v_mul_lo_u32 v5, v32, 24
	v_add_u32_e32 v167, 0, v6
	v_add_u32_e32 v168, s25, v6
	v_lshlrev_b32_e32 v6, 5, v153
	v_lshlrev_b32_e32 v82, 1, v147
	v_lshlrev_b32_e32 v84, 1, v150
	v_lshlrev_b32_e32 v86, 1, v153
	v_lshlrev_b32_e32 v88, 1, v1
	v_lshlrev_b32_e32 v90, 1, v2
	v_lshlrev_b32_e32 v92, 1, v3
	v_lshlrev_b32_e32 v94, 1, v4
	s_mov_b32 s5, s4
	s_mov_b32 s58, -1.0
	s_mov_b32 s62, 0xb9c90fda
	s_mov_b32 s64, -0.5
	v_ashrrev_i32_e32 v35, 31, v34
	v_cmp_ne_u32_e32 vcc, 0, v34
	v_ashrrev_i32_e32 v37, 31, v36
	v_ashrrev_i32_e32 v39, 31, v38
	v_ashrrev_i32_e32 v41, 31, v40
	v_cmp_ne_u32_e64 s[6:7], 0, v40
	v_ashrrev_i32_e32 v43, 31, v42
	v_ashrrev_i32_e32 v45, 31, v44
	v_ashrrev_i32_e32 v47, 31, v46
	v_cmp_ne_u32_e64 s[8:9], 0, v46
	v_ashrrev_i32_e32 v49, 31, v48
	v_ashrrev_i32_e32 v51, 31, v50
	v_ashrrev_i32_e32 v53, 31, v52
	v_cmp_ne_u32_e64 s[10:11], 0, v52
	v_ashrrev_i32_e32 v55, 31, v54
	v_ashrrev_i32_e32 v57, 31, v56
	s_movk_i32 s28, 0x1000
	v_ashrrev_i32_e32 v59, 31, v58
	v_cmp_ne_u32_e64 s[12:13], 0, v58
	v_ashrrev_i32_e32 v61, 31, v60
	v_ashrrev_i32_e32 v63, 31, v62
	v_ashrrev_i32_e32 v65, 31, v64
	v_cmp_ne_u32_e64 s[14:15], 0, v64
	v_ashrrev_i32_e32 v67, 31, v66
	v_ashrrev_i32_e32 v69, 31, v68
	v_ashrrev_i32_e32 v71, 31, v70
	v_cmp_ne_u32_e64 s[16:17], 0, v70
	v_ashrrev_i32_e32 v73, 31, v72
	v_ashrrev_i32_e32 v75, 31, v74
	v_ashrrev_i32_e32 v77, 31, v76
	v_cmp_ne_u32_e64 s[18:19], 0, v76
	v_ashrrev_i32_e32 v79, 31, v78
	v_ashrrev_i32_e32 v81, 31, v80
	v_add_u32_e32 v146, 0x8000, v33
	v_lshl_add_u32 v148, v147, 3, s25
	v_add_u32_e32 v149, 0x9000, v33
	v_lshl_add_u32 v151, v150, 3, s25
	v_add_u32_e32 v152, 0xa000, v33
	v_lshl_add_u32 v154, v153, 3, s25
	v_add_u32_e32 v155, 0xb000, v33
	v_lshl_add_u32 v156, v1, 3, s25
	v_add_u32_e32 v157, 0xc000, v33
	v_lshl_add_u32 v158, v2, 3, s25
	v_add_u32_e32 v159, 0xd000, v33
	v_lshl_add_u32 v160, v3, 3, s25
	v_add_u32_e32 v161, 0xe000, v33
	v_lshl_add_u32 v162, v4, 3, s25
	v_add_u32_e32 v163, 0xf000, v33
	v_add_u32_e32 v164, s25, v144
	v_add_u32_e32 v169, 0, v6
	v_add_u32_e32 v170, s25, v6
	v_add_u32_e32 v171, 0, v0
	v_add_u32_e32 v172, s25, v0
	v_lshl_add_u32 v173, v40, 3, s25
	v_lshl_add_u32 v174, v46, 3, s25
	v_lshl_add_u32 v175, v52, 3, s25
	v_lshl_add_u32 v176, v58, 3, s25
	v_lshl_add_u32 v177, v64, 3, s25
	v_lshl_add_u32 v178, v70, 3, s25
	v_lshl_add_u32 v179, v76, 3, s25
	v_ashrrev_i32_e32 v83, 31, v82
	v_ashrrev_i32_e32 v85, 31, v84
	v_ashrrev_i32_e32 v87, 31, v86
	v_ashrrev_i32_e32 v89, 31, v88
	v_ashrrev_i32_e32 v91, 31, v90
	v_ashrrev_i32_e32 v93, 31, v92
	v_ashrrev_i32_e32 v95, 31, v94
	v_mov_b64_e32 v[182:183], s[4:5]
	s_add_i32 s29, 0, 0x20000
	s_mov_b32 s59, 1.0
	v_add_u32_e32 v180, v145, v5
	s_movk_i32 s33, 0x1001
	s_mov_b32 s60, 0x3f7fffff
	s_mov_b32 s63, 0x39c90fda
	s_mov_b32 s65, 0.5
	s_mov_b32 s66, 0x39000000
	v_mov_b32_e32 v181, 0
	s_mov_b32 s68, s2
	s_ashr_i32 s69, s68, 31
	s_lshl_b64 s[0:1], s[68:69], 15
	s_add_u32 s20, s50, s0
	s_addc_u32 s21, s51, s1
	s_add_u32 s4, s20, 0x4000000
	s_addc_u32 s5, s21, 0
	s_add_u32 s36, s54, s0
	v_lshlrev_b64 v[0:1], 2, v[34:35]
	s_addc_u32 s37, s55, s1
	v_lshl_add_u64 v[2:3], s[20:21], 0, v[0:1]
	v_lshl_add_u64 v[96:97], s[36:37], 0, v[0:1]
	global_load_dwordx2 v[208:209], v[2:3], off
	global_load_dwordx2 v[206:207], v[96:97], off
	v_mov_b32_e32 v212, 0
	s_and_saveexec_b64 s[0:1], vcc
	s_cbranch_execz .Lfft_pre_1378
	v_lshl_add_u64 v[2:3], v[36:37], 2, s[4:5]
	global_load_dword v212, v[2:3], off
.Lfft_pre_1378:
	s_or_b64 exec, exec, s[0:1]
	v_lshl_add_u64 v[6:7], v[38:39], 2, s[4:5]
	v_lshlrev_b64 v[8:9], 2, v[40:41]
	v_lshl_add_u64 v[10:11], s[20:21], 0, v[8:9]
	v_lshl_add_u64 v[98:99], s[36:37], 0, v[8:9]
	global_load_dword v213, v[6:7], off
	global_load_dwordx2 v[210:211], v[10:11], off
	s_nop 0
	global_load_dwordx2 v[216:217], v[98:99], off
	v_mov_b32_e32 v214, 0
	s_and_saveexec_b64 s[0:1], s[6:7]
	s_cbranch_execz .Lfft_pre_1380
	v_lshl_add_u64 v[10:11], v[42:43], 2, s[4:5]
	global_load_dword v214, v[10:11], off
.Lfft_pre_1380:
	s_or_b64 exec, exec, s[0:1]
	v_lshl_add_u64 v[12:13], v[44:45], 2, s[4:5]
	v_lshlrev_b64 v[14:15], 2, v[46:47]
	v_lshl_add_u64 v[16:17], s[20:21], 0, v[14:15]
	v_lshl_add_u64 v[100:101], s[36:37], 0, v[14:15]
	global_load_dword v215, v[12:13], off
	s_nop 0
	global_load_dwordx2 v[220:221], v[16:17], off
	global_load_dwordx2 v[218:219], v[100:101], off
	v_mov_b32_e32 v226, 0
	v_mov_b32_e32 v224, 0
	s_and_saveexec_b64 s[0:1], s[8:9]
	s_cbranch_execz .Lfft_pre_1382
	v_lshl_add_u64 v[16:17], v[48:49], 2, s[4:5]
	global_load_dword v224, v[16:17], off
.Lfft_pre_1382:
	s_or_b64 exec, exec, s[0:1]
	v_lshl_add_u64 v[20:21], v[50:51], 2, s[4:5]
	v_lshlrev_b64 v[22:23], 2, v[52:53]
	v_lshl_add_u64 v[24:25], s[20:21], 0, v[22:23]
	v_lshl_add_u64 v[102:103], s[36:37], 0, v[22:23]
	global_load_dword v225, v[20:21], off
	global_load_dwordx2 v[222:223], v[24:25], off
	s_nop 0
	global_load_dwordx2 v[228:229], v[102:103], off
	s_and_saveexec_b64 s[0:1], s[10:11]
	s_cbranch_execz .Lfft_pre_1384
	v_lshl_add_u64 v[14:15], v[54:55], 2, s[4:5]
	global_load_dword v226, v[14:15], off
.Lfft_pre_1384:
	s_or_b64 exec, exec, s[0:1]
	v_lshl_add_u64 v[24:25], v[56:57], 2, s[4:5]
	v_lshlrev_b64 v[26:27], 2, v[58:59]
	v_lshl_add_u64 v[28:29], s[20:21], 0, v[26:27]
	v_lshl_add_u64 v[104:105], s[36:37], 0, v[26:27]
	global_load_dword v227, v[24:25], off
	s_nop 0
	global_load_dwordx2 v[232:233], v[28:29], off
	global_load_dwordx2 v[230:231], v[104:105], off
	v_mov_b32_e32 v238, 0
	v_mov_b32_e32 v236, 0
	s_and_saveexec_b64 s[0:1], s[12:13]
	s_cbranch_execz .Lfft_pre_1386
	v_lshl_add_u64 v[28:29], v[60:61], 2, s[4:5]
	global_load_dword v236, v[28:29], off
.Lfft_pre_1386:
	s_or_b64 exec, exec, s[0:1]
	v_lshl_add_u64 v[108:109], v[62:63], 2, s[4:5]
	v_lshlrev_b64 v[106:107], 2, v[64:65]
	v_lshl_add_u64 v[110:111], s[20:21], 0, v[106:107]
	v_lshl_add_u64 v[106:107], s[36:37], 0, v[106:107]
	global_load_dword v237, v[108:109], off
	global_load_dwordx2 v[234:235], v[110:111], off
	global_load_dwordx2 v[240:241], v[106:107], off
	s_and_saveexec_b64 s[0:1], s[14:15]
	s_cbranch_execz .Lfft_pre_1388
	v_lshl_add_u64 v[26:27], v[66:67], 2, s[4:5]
	global_load_dword v238, v[26:27], off
.Lfft_pre_1388:
	s_or_b64 exec, exec, s[0:1]
	v_lshl_add_u64 v[110:111], v[68:69], 2, s[4:5]
	v_lshlrev_b64 v[108:109], 2, v[70:71]
	v_lshl_add_u64 v[116:117], s[20:21], 0, v[108:109]
	v_lshl_add_u64 v[108:109], s[36:37], 0, v[108:109]
	global_load_dword v239, v[110:111], off
	global_load_dwordx2 v[244:245], v[116:117], off
	global_load_dwordx2 v[242:243], v[108:109], off
	v_mov_b32_e32 v252, 0
	v_mov_b32_e32 v250, 0
	s_and_saveexec_b64 s[0:1], s[16:17]
	s_cbranch_execz .Lfft_pre_1390
	v_lshl_add_u64 v[110:111], v[72:73], 2, s[4:5]
	global_load_dword v250, v[110:111], off
.Lfft_pre_1390:
	s_or_b64 exec, exec, s[0:1]
	v_lshlrev_b64 v[110:111], 2, v[76:77]
	v_lshl_add_u64 v[124:125], v[74:75], 2, s[4:5]
	v_lshl_add_u64 v[126:127], s[20:21], 0, v[110:111]
	v_lshl_add_u64 v[110:111], s[36:37], 0, v[110:111]
	global_load_dword v251, v[124:125], off
	s_nop 0
	global_load_dwordx2 v[246:247], v[126:127], off
	s_nop 0
	global_load_dwordx2 v[248:249], v[110:111], off
	s_and_saveexec_b64 s[0:1], s[18:19]
	s_cbranch_execz .Lfft_pre_1392
	v_lshl_add_u64 v[116:117], v[78:79], 2, s[4:5]
	global_load_dword v252, v[116:117], off
.Lfft_pre_1392:
	s_or_b64 exec, exec, s[0:1]
	v_lshl_add_u64 v[128:129], v[80:81], 2, s[4:5]
	global_load_dword v253, v[128:129], off
.LBB0_1376:
	s_ashr_i32 s69, s68, 31
	s_lshl_b64 s[0:1], s[68:69], 15
	s_add_u32 s20, s50, s0
	s_addc_u32 s21, s51, s1
	s_add_u32 s4, s20, 0x4000000
	s_addc_u32 s5, s21, 0
	s_add_u32 s36, s54, s0
	s_addc_u32 s37, s55, s1
	v_lshlrev_b64 v[0:1], 2, v[34:35]
	v_lshl_add_u64 v[96:97], s[36:37], 0, v[0:1]
	v_lshlrev_b64 v[0:1], 2, v[40:41]
	v_lshl_add_u64 v[98:99], s[36:37], 0, v[0:1]
	v_lshlrev_b64 v[0:1], 2, v[46:47]
	v_lshl_add_u64 v[100:101], s[36:37], 0, v[0:1]
	v_lshlrev_b64 v[0:1], 2, v[52:53]
	v_lshl_add_u64 v[102:103], s[36:37], 0, v[0:1]
	v_lshlrev_b64 v[0:1], 2, v[58:59]
	v_lshl_add_u64 v[104:105], s[36:37], 0, v[0:1]
	v_lshlrev_b64 v[0:1], 2, v[64:65]
	v_lshl_add_u64 v[106:107], s[36:37], 0, v[0:1]
	v_lshlrev_b64 v[0:1], 2, v[70:71]
	v_lshl_add_u64 v[108:109], s[36:37], 0, v[0:1]
	v_lshlrev_b64 v[0:1], 2, v[76:77]
	v_lshl_add_u64 v[110:111], s[36:37], 0, v[0:1]
	s_lshl_b64 s[70:71], s[68:69], 13
	s_mov_b32 s0, 1
	s_waitcnt vmcnt(0)
	ds_write_b64 v33, v[206:207]
	ds_write_b64 v146, v[182:183]
	ds_write2st64_b64 v145, v[208:209], v[210:211] offset1:8
	ds_write2st64_b64 v145, v[212:213], v[214:215] offset0:64 offset1:72
	ds_write_b64 v148, v[216:217]
	ds_write_b64 v149, v[182:183]
	ds_write_b64 v151, v[218:219]
	ds_write_b64 v152, v[182:183]
	ds_write2st64_b64 v145, v[220:221], v[222:223] offset0:16 offset1:24
	ds_write2st64_b64 v145, v[224:225], v[226:227] offset0:80 offset1:88
	ds_write_b64 v154, v[228:229]
	ds_write_b64 v155, v[182:183]
	ds_write_b64 v156, v[230:231]
	ds_write_b64 v157, v[182:183]
	ds_write2st64_b64 v145, v[232:233], v[234:235] offset0:32 offset1:40
	ds_write2st64_b64 v145, v[236:237], v[238:239] offset0:96 offset1:104
	ds_write_b64 v158, v[240:241]
	ds_write_b64 v159, v[182:183]
	ds_write_b64 v160, v[242:243]
	ds_write_b64 v161, v[182:183]
	ds_write2st64_b64 v145, v[244:245], v[246:247] offset0:48 offset1:56
	ds_write_b64 v162, v[248:249]
	ds_write_b64 v163, v[182:183]
	ds_write2st64_b64 v145, v[250:251], v[252:253] offset0:112 offset1:120
	s_waitcnt lgkmcnt(0)
	s_barrier
	s_add_i32 s0, s68, s30
	s_ashr_i32 s1, s0, 31
	s_lshl_b64 s[0:1], s[0:1], 15
	s_add_u32 s20, s50, s0
	s_addc_u32 s21, s51, s1
	s_add_u32 s4, s20, 0x4000000
	s_addc_u32 s5, s21, 0
	s_add_u32 s36, s54, s0
	v_lshlrev_b64 v[0:1], 2, v[34:35]
	s_addc_u32 s37, s55, s1
	v_lshl_add_u64 v[2:3], s[20:21], 0, v[0:1]
	v_lshl_add_u64 v[130:131], s[36:37], 0, v[0:1]
	global_load_dwordx2 v[208:209], v[2:3], off
	global_load_dwordx2 v[206:207], v[130:131], off
	v_mov_b32_e32 v212, 0
	s_and_saveexec_b64 s[0:1], vcc
	s_cbranch_execz .Lfft_nxt_1378
	v_lshl_add_u64 v[2:3], v[36:37], 2, s[4:5]
	global_load_dword v212, v[2:3], off
.Lfft_nxt_1378:
	s_or_b64 exec, exec, s[0:1]
	v_lshl_add_u64 v[6:7], v[38:39], 2, s[4:5]
	v_lshlrev_b64 v[8:9], 2, v[40:41]
	v_lshl_add_u64 v[10:11], s[20:21], 0, v[8:9]
	v_lshl_add_u64 v[132:133], s[36:37], 0, v[8:9]
	global_load_dword v213, v[6:7], off
	global_load_dwordx2 v[210:211], v[10:11], off
	s_nop 0
	global_load_dwordx2 v[216:217], v[132:133], off
	v_mov_b32_e32 v214, 0
	s_and_saveexec_b64 s[0:1], s[6:7]
	s_cbranch_execz .Lfft_nxt_1380
	v_lshl_add_u64 v[10:11], v[42:43], 2, s[4:5]
	global_load_dword v214, v[10:11], off
.Lfft_nxt_1380:
	s_or_b64 exec, exec, s[0:1]
	v_lshl_add_u64 v[12:13], v[44:45], 2, s[4:5]
	v_lshlrev_b64 v[14:15], 2, v[46:47]
	v_lshl_add_u64 v[16:17], s[20:21], 0, v[14:15]
	v_lshl_add_u64 v[134:135], s[36:37], 0, v[14:15]
	global_load_dword v215, v[12:13], off
	s_nop 0
	global_load_dwordx2 v[220:221], v[16:17], off
	global_load_dwordx2 v[218:219], v[134:135], off
	v_mov_b32_e32 v226, 0
	v_mov_b32_e32 v224, 0
	s_and_saveexec_b64 s[0:1], s[8:9]
	s_cbranch_execz .Lfft_nxt_1382
	v_lshl_add_u64 v[16:17], v[48:49], 2, s[4:5]
	global_load_dword v224, v[16:17], off
.Lfft_nxt_1382:
	s_or_b64 exec, exec, s[0:1]
	v_lshl_add_u64 v[20:21], v[50:51], 2, s[4:5]
	v_lshlrev_b64 v[22:23], 2, v[52:53]
	v_lshl_add_u64 v[24:25], s[20:21], 0, v[22:23]
	v_lshl_add_u64 v[136:137], s[36:37], 0, v[22:23]
	global_load_dword v225, v[20:21], off
	global_load_dwordx2 v[222:223], v[24:25], off
	s_nop 0
	global_load_dwordx2 v[228:229], v[136:137], off
	s_and_saveexec_b64 s[0:1], s[10:11]
	s_cbranch_execz .Lfft_nxt_1384
	v_lshl_add_u64 v[14:15], v[54:55], 2, s[4:5]
	global_load_dword v226, v[14:15], off
.Lfft_nxt_1384:
	s_or_b64 exec, exec, s[0:1]
	v_lshl_add_u64 v[24:25], v[56:57], 2, s[4:5]
	v_lshlrev_b64 v[26:27], 2, v[58:59]
	v_lshl_add_u64 v[28:29], s[20:21], 0, v[26:27]
	v_lshl_add_u64 v[138:139], s[36:37], 0, v[26:27]
	global_load_dword v227, v[24:25], off
	s_nop 0
	global_load_dwordx2 v[232:233], v[28:29], off
	global_load_dwordx2 v[230:231], v[138:139], off
	v_mov_b32_e32 v238, 0
	v_mov_b32_e32 v236, 0
	s_and_saveexec_b64 s[0:1], s[12:13]
	s_cbranch_execz .Lfft_nxt_1386
	v_lshl_add_u64 v[28:29], v[60:61], 2, s[4:5]
	global_load_dword v236, v[28:29], off
.Lfft_nxt_1386:
	s_or_b64 exec, exec, s[0:1]
	v_lshl_add_u64 v[142:143], v[62:63], 2, s[4:5]
	v_lshlrev_b64 v[140:141], 2, v[64:65]
	v_lshl_add_u64 v[184:185], s[20:21], 0, v[140:141]
	v_lshl_add_u64 v[140:141], s[36:37], 0, v[140:141]
	global_load_dword v237, v[142:143], off
	global_load_dwordx2 v[234:235], v[184:185], off
	global_load_dwordx2 v[240:241], v[140:141], off
	s_and_saveexec_b64 s[0:1], s[14:15]
	s_cbranch_execz .Lfft_nxt_1388
	v_lshl_add_u64 v[26:27], v[66:67], 2, s[4:5]
	global_load_dword v238, v[26:27], off
.Lfft_nxt_1388:
	s_or_b64 exec, exec, s[0:1]
	v_lshl_add_u64 v[184:185], v[68:69], 2, s[4:5]
	v_lshlrev_b64 v[142:143], 2, v[70:71]
	v_lshl_add_u64 v[116:117], s[20:21], 0, v[142:143]
	v_lshl_add_u64 v[142:143], s[36:37], 0, v[142:143]
	global_load_dword v239, v[184:185], off
	global_load_dwordx2 v[244:245], v[116:117], off
	global_load_dwordx2 v[242:243], v[142:143], off
	v_mov_b32_e32 v252, 0
	v_mov_b32_e32 v250, 0
	s_and_saveexec_b64 s[0:1], s[16:17]
	s_cbranch_execz .Lfft_nxt_1390
	v_lshl_add_u64 v[184:185], v[72:73], 2, s[4:5]
	global_load_dword v250, v[184:185], off
.Lfft_nxt_1390:
	s_or_b64 exec, exec, s[0:1]
	v_lshlrev_b64 v[184:185], 2, v[76:77]
	v_lshl_add_u64 v[124:125], v[74:75], 2, s[4:5]
	v_lshl_add_u64 v[126:127], s[20:21], 0, v[184:185]
	v_lshl_add_u64 v[184:185], s[36:37], 0, v[184:185]
	global_load_dword v251, v[124:125], off
	s_nop 0
	global_load_dwordx2 v[246:247], v[126:127], off
	s_nop 0
	global_load_dwordx2 v[248:249], v[184:185], off
	s_and_saveexec_b64 s[0:1], s[18:19]
	s_cbranch_execz .Lfft_nxt_1392
	v_lshl_add_u64 v[116:117], v[78:79], 2, s[4:5]
	global_load_dword v252, v[116:117], off
.Lfft_nxt_1392:
	s_or_b64 exec, exec, s[0:1]
	v_lshl_add_u64 v[128:129], v[80:81], 2, s[4:5]
	global_load_dword v253, v[128:129], off
	s_mov_b32 s0, 1
